# combo5 + pool phase: all conditional history-row loads of an item issued up front instead of load/wait per row
# speedup vs baseline: 1.0137x; 1.0137x over previous
; __device__ __forceinline__ float bf2f(short b) { return __uint_as_float(((unsigned)(unsigned short)b) << 16); }
; template <int W>
; __device__ __forceinline__ void pool_item(const Params& p, const bf16_t* __restrict__ U, bf16_t* __restrict__ PO, bool samp, int b, int rowb, int t0, int c4) {
;     constexpr int NR = 8;
;     const float* hist = p.in[6] + (size_t)b * 15 * 1024;
;     f32x4 r[W + NR - 1];
; #pragma unroll
;     for (int j = 0; j < W + NR - 1; ++j) {
;         const int tp = t0 - W + 1 + j;
;         if (tp >= 0) { const bf16x4 v = *(const bf16x4*)(U + (size_t)(rowb + tp) * DM + c4); r[j] = (f32x4){bf2f(v[0]), bf2f(v[1]), bf2f(v[2]), bf2f(v[3])}; }
;         else if (samp) r[j] = *(const f32x4*)(hist + (size_t)(15 + tp) * 1024 + c4);
;         else r[j] = (f32x4){0.f, 0.f, 0.f, 0.f};
;     }
; __device__ __forceinline__ void phase_pool(const Params& p) {
;     ...
;         if (g == 0) pool_item<2>(p, U, PO, samp, b, rowb, t0, c4);
;         else if (g == 1) pool_item<4>(p, U, PO, samp, b, rowb, t0, c4);
;         else if (g == 2) pool_item<8>(p, U, PO, samp, b, rowb, t0, c4);
;         else pool_item<16>(p, U, PO, samp, b, rowb, t0, c4);
.LBB0_996:
	v_ashrrev_i32_e32 v0, 8, v156
	v_cmp_lt_i32_e64 s[40:41], s30, v0
	v_cmp_gt_i32_e64 s[2:3], s31, v0
	s_and_saveexec_b64 s[0:1], s[2:3]
	s_xor_b64 s[0:1], exec, s[0:1]
	v_ashrrev_i32_e32 v91, 16, v156
	v_lshlrev_b32_e32 v76, 11, v91
	s_or_saveexec_b64 s[0:1], s[0:1]
	s_waitcnt lgkmcnt(0)
	v_mov_b32_e32 v1, 0x7f8
	s_xor_b64 exec, exec, s[0:1]
	v_add_u32_e32 v1, 0xfffff800, v0
	v_lshrrev_b32_e32 v91, 1, v1
	v_lshl_add_u32 v76, v91, 4, v97
	v_mov_b32_e32 v1, 8
	s_or_b64 exec, exec, s[0:1]
	v_and_b32_e32 v60, 0x3fc, v96
	v_lshlrev_b32_e32 v0, 3, v0
	v_and_b32_e32 v101, v1, v0
	v_cmp_lt_u32_e32 vcc, s34, v60
	s_mov_b64 s[4:5], 0
	s_and_saveexec_b64 s[0:1], vcc
	s_xor_b64 s[42:43], exec, s[0:1]
	s_cbranch_execz .LBB0_1059
	v_mov_b64_e32 v[0:1], s[64:65]
	v_lshrrev_b32_e32 v3, 8, v60
	v_lshlrev_b32_e32 v64, 1, v60
	v_mov_b32_e32 v65, v61
	v_mad_i64_i32 v[0:1], s[0:1], v91, s35, v[0:1]
	v_lshlrev_b32_e32 v62, 2, v60
	v_mov_b32_e32 v63, v61
	v_lshl_add_u64 v[66:67], s[10:11], 0, v[64:65]
	v_lshl_add_u64 v[68:69], v[0:1], 0, v[62:63]
	v_cmp_lt_i32_e32 vcc, 1, v3
	s_mov_b64 s[52:53], 0
	s_and_saveexec_b64 s[0:1], vcc
	s_xor_b64 s[46:47], exec, s[0:1]
	s_cbranch_execz .LBB0_1253
	v_cmp_ne_u32_e32 vcc, 2, v3
	s_mov_b64 s[54:55], 0
	s_and_saveexec_b64 s[0:1], vcc
	s_xor_b64 s[52:53], exec, s[0:1]
	s_cbranch_execz .LBB0_1172
	v_add_u32_e32 v214, v101, v76
	v_ashrrev_i32_e32 v215, 31, v214
	v_lshlrev_b64 v[214:215], 11, v[214:215]
	v_lshl_add_u64 v[214:215], v[66:67], 0, v[214:215]
	s_mov_b32 s98, 0xffffe000
	s_mov_b32 s99, -1
	global_load_dwordx2 v[212:213], v[214:215], off offset:-4096
	v_lshl_add_u64 v[214:215], v[214:215], 0, s[98:99]
	global_load_dwordx2 v[210:211], v[214:215], off offset:2048
	global_load_dwordx2 v[208:209], v[214:215], off
	global_load_dwordx2 v[206:207], v[214:215], off offset:-2048
	global_load_dwordx2 v[204:205], v[214:215], off offset:-4096
	v_lshl_add_u64 v[214:215], v[214:215], 0, s[98:99]
	global_load_dwordx2 v[202:203], v[214:215], off offset:2048
	global_load_dwordx2 v[200:201], v[214:215], off
	global_load_dwordx2 v[198:199], v[214:215], off offset:-2048
	global_load_dwordx2 v[196:197], v[214:215], off offset:-4096
	v_lshl_add_u64 v[214:215], v[214:215], 0, s[98:99]
	global_load_dwordx2 v[194:195], v[214:215], off offset:2048
	global_load_dwordx2 v[192:193], v[214:215], off
	global_load_dwordx2 v[190:191], v[214:215], off offset:-2048
	global_load_dwordx2 v[188:189], v[214:215], off offset:-4096
	v_lshl_add_u64 v[214:215], v[214:215], 0, s[98:99]
	global_load_dwordx2 v[186:187], v[214:215], off offset:2048
	v_cmp_gt_u32_e32 vcc, 15, v101
	s_and_saveexec_b64 s[0:1], vcc
	s_xor_b64 s[0:1], exec, s[0:1]
	s_cbranch_execz .LBB0_1007
	v_mov_b32_e32 v27, 0
	v_mov_b32_e32 v26, 0
	v_mov_b32_e32 v25, 0
	v_mov_b32_e32 v24, 0
	s_and_saveexec_b64 s[4:5], s[40:41]
	s_cbranch_execz .LBB0_1006
	v_lshlrev_b32_e32 v0, 12, v101
	v_mov_b32_e32 v1, v61
	v_lshl_add_u64 v[0:1], v[68:69], 0, v[0:1]
	global_load_dwordx4 v[24:27], v[0:1], off

; __device__ __forceinline__ float bf2f(short b) { return __uint_as_float(((unsigned)(unsigned short)b) << 16); }
; template <int W>
; __device__ __forceinline__ void pool_item(const Params& p, const bf16_t* __restrict__ U, bf16_t* __restrict__ PO, bool samp, int b, int rowb, int t0, int c4) {
;     ...
;     for (int j = 0; j < W + NR - 1; ++j) {
;         const int tp = t0 - W + 1 + j;
;         if (tp >= 0) { const bf16x4 v = *(const bf16x4*)(U + (size_t)(rowb + tp) * DM + c4); r[j] = (f32x4){bf2f(v[0]), bf2f(v[1]), bf2f(v[2]), bf2f(v[3])}; }
;         else if (samp) r[j] = *(const f32x4*)(hist + (size_t)(15 + tp) * 1024 + c4);
;         else r[j] = (f32x4){0.f, 0.f, 0.f, 0.f};
.LBB0_1007:
	s_andn2_saveexec_b64 s[0:1], s[0:1]
	s_cbranch_execz .LBB0_1009
	v_add_u32_e32 v0, v101, v76
	v_ashrrev_i32_e32 v1, 31, v0
	v_lshlrev_b64 v[0:1], 11, v[0:1]
	v_lshl_add_u64 v[0:1], v[66:67], 0, v[0:1]
	v_add_co_u32_e32 v0, vcc, 0xffff9000, v0
	s_nop 1
	v_addc_co_u32_e32 v1, vcc, -1, v1, vcc
	s_waitcnt vmcnt(0)
	v_and_b32_e32 v25, 0xffff0000, v186
	v_and_b32_e32 v27, 0xffff0000, v187
	v_lshlrev_b32_e32 v24, 16, v186
	v_lshlrev_b32_e32 v26, 16, v187

; __device__ __forceinline__ float bf2f(short b) { return __uint_as_float(((unsigned)(unsigned short)b) << 16); }
; template <int W>
; __device__ __forceinline__ void pool_item(const Params& p, const bf16_t* __restrict__ U, bf16_t* __restrict__ PO, bool samp, int b, int rowb, int t0, int c4) {
;     ...
;     for (int j = 0; j < W + NR - 1; ++j) {
;         const int tp = t0 - W + 1 + j;
;         if (tp >= 0) { const bf16x4 v = *(const bf16x4*)(U + (size_t)(rowb + tp) * DM + c4); r[j] = (f32x4){bf2f(v[0]), bf2f(v[1]), bf2f(v[2]), bf2f(v[3])}; }
;         else if (samp) r[j] = *(const f32x4*)(hist + (size_t)(15 + tp) * 1024 + c4);
;         else r[j] = (f32x4){0.f, 0.f, 0.f, 0.f};
.LBB0_1013:
	s_andn2_saveexec_b64 s[0:1], s[0:1]
	s_cbranch_execz .LBB0_1015
	v_add_u32_e32 v0, v101, v76
	v_ashrrev_i32_e32 v1, 31, v0
	v_lshlrev_b64 v[0:1], 11, v[0:1]
	v_lshl_add_u64 v[0:1], v[66:67], 0, v[0:1]
	v_add_co_u32_e32 v0, vcc, 0xffff9000, v0
	s_nop 1
	v_addc_co_u32_e32 v1, vcc, -1, v1, vcc
	s_waitcnt vmcnt(0)
	v_and_b32_e32 v21, 0xffff0000, v188
	v_and_b32_e32 v23, 0xffff0000, v189
	v_lshlrev_b32_e32 v20, 16, v188
	v_lshlrev_b32_e32 v22, 16, v189

; __device__ __forceinline__ float bf2f(short b) { return __uint_as_float(((unsigned)(unsigned short)b) << 16); }
; template <int W>
; __device__ __forceinline__ void pool_item(const Params& p, const bf16_t* __restrict__ U, bf16_t* __restrict__ PO, bool samp, int b, int rowb, int t0, int c4) {
;     ...
;     for (int j = 0; j < W + NR - 1; ++j) {
;         const int tp = t0 - W + 1 + j;
;         if (tp >= 0) { const bf16x4 v = *(const bf16x4*)(U + (size_t)(rowb + tp) * DM + c4); r[j] = (f32x4){bf2f(v[0]), bf2f(v[1]), bf2f(v[2]), bf2f(v[3])}; }
;         else if (samp) r[j] = *(const f32x4*)(hist + (size_t)(15 + tp) * 1024 + c4);
;         else r[j] = (f32x4){0.f, 0.f, 0.f, 0.f};
.LBB0_1019:
	s_andn2_saveexec_b64 s[0:1], s[0:1]
	s_cbranch_execz .LBB0_1021
	v_add_u32_e32 v0, v101, v76
	v_ashrrev_i32_e32 v1, 31, v0
	v_lshlrev_b64 v[0:1], 11, v[0:1]
	v_lshl_add_u64 v[0:1], v[66:67], 0, v[0:1]
	v_add_co_u32_e32 v0, vcc, 0xffffa000, v0
	s_nop 1
	v_addc_co_u32_e32 v1, vcc, -1, v1, vcc
	s_waitcnt vmcnt(0)
	v_and_b32_e32 v17, 0xffff0000, v190
	v_and_b32_e32 v19, 0xffff0000, v191
	v_lshlrev_b32_e32 v16, 16, v190
	v_lshlrev_b32_e32 v18, 16, v191

; __device__ __forceinline__ float bf2f(short b) { return __uint_as_float(((unsigned)(unsigned short)b) << 16); }
; template <int W>
; __device__ __forceinline__ void pool_item(const Params& p, const bf16_t* __restrict__ U, bf16_t* __restrict__ PO, bool samp, int b, int rowb, int t0, int c4) {
;     ...
;     for (int j = 0; j < W + NR - 1; ++j) {
;         const int tp = t0 - W + 1 + j;
;         if (tp >= 0) { const bf16x4 v = *(const bf16x4*)(U + (size_t)(rowb + tp) * DM + c4); r[j] = (f32x4){bf2f(v[0]), bf2f(v[1]), bf2f(v[2]), bf2f(v[3])}; }
;         else if (samp) r[j] = *(const f32x4*)(hist + (size_t)(15 + tp) * 1024 + c4);
;         else r[j] = (f32x4){0.f, 0.f, 0.f, 0.f};
.LBB0_1025:
	s_andn2_saveexec_b64 s[0:1], s[0:1]
	s_cbranch_execz .LBB0_1027
	v_add_u32_e32 v0, v101, v76
	v_ashrrev_i32_e32 v1, 31, v0
	v_lshlrev_b64 v[0:1], 11, v[0:1]
	v_lshl_add_u64 v[0:1], v[66:67], 0, v[0:1]
	v_add_co_u32_e32 v0, vcc, 0xffffa000, v0
	s_nop 1
	v_addc_co_u32_e32 v1, vcc, -1, v1, vcc
	s_waitcnt vmcnt(0)
	v_and_b32_e32 v13, 0xffff0000, v192
	v_and_b32_e32 v15, 0xffff0000, v193
	v_lshlrev_b32_e32 v12, 16, v192
	v_lshlrev_b32_e32 v14, 16, v193

; __device__ __forceinline__ float bf2f(short b) { return __uint_as_float(((unsigned)(unsigned short)b) << 16); }
; template <int W>
; __device__ __forceinline__ void pool_item(const Params& p, const bf16_t* __restrict__ U, bf16_t* __restrict__ PO, bool samp, int b, int rowb, int t0, int c4) {
;     ...
;     for (int j = 0; j < W + NR - 1; ++j) {
;         const int tp = t0 - W + 1 + j;
;         if (tp >= 0) { const bf16x4 v = *(const bf16x4*)(U + (size_t)(rowb + tp) * DM + c4); r[j] = (f32x4){bf2f(v[0]), bf2f(v[1]), bf2f(v[2]), bf2f(v[3])}; }
;         else if (samp) r[j] = *(const f32x4*)(hist + (size_t)(15 + tp) * 1024 + c4);
;         else r[j] = (f32x4){0.f, 0.f, 0.f, 0.f};
.LBB0_1031:
	s_andn2_saveexec_b64 s[0:1], s[0:1]
	s_cbranch_execz .LBB0_1033
	v_add_u32_e32 v0, v101, v76
	v_ashrrev_i32_e32 v1, 31, v0
	v_lshlrev_b64 v[0:1], 11, v[0:1]
	v_lshl_add_u64 v[0:1], v[66:67], 0, v[0:1]
	v_add_co_u32_e32 v0, vcc, 0xffffb000, v0
	s_nop 1
	v_addc_co_u32_e32 v1, vcc, -1, v1, vcc
	s_waitcnt vmcnt(0)
	v_and_b32_e32 v9, 0xffff0000, v194
	v_and_b32_e32 v11, 0xffff0000, v195
	v_lshlrev_b32_e32 v8, 16, v194
	v_lshlrev_b32_e32 v10, 16, v195

; __device__ __forceinline__ float bf2f(short b) { return __uint_as_float(((unsigned)(unsigned short)b) << 16); }
; template <int W>
; __device__ __forceinline__ void pool_item(const Params& p, const bf16_t* __restrict__ U, bf16_t* __restrict__ PO, bool samp, int b, int rowb, int t0, int c4) {
;     ...
;     for (int j = 0; j < W + NR - 1; ++j) {
;         const int tp = t0 - W + 1 + j;
;         if (tp >= 0) { const bf16x4 v = *(const bf16x4*)(U + (size_t)(rowb + tp) * DM + c4); r[j] = (f32x4){bf2f(v[0]), bf2f(v[1]), bf2f(v[2]), bf2f(v[3])}; }
;         else if (samp) r[j] = *(const f32x4*)(hist + (size_t)(15 + tp) * 1024 + c4);
;         else r[j] = (f32x4){0.f, 0.f, 0.f, 0.f};
.LBB0_1037:
	s_andn2_saveexec_b64 s[0:1], s[0:1]
	s_cbranch_execz .LBB0_1039
	v_add_u32_e32 v0, v101, v76
	v_ashrrev_i32_e32 v1, 31, v0
	v_lshlrev_b64 v[0:1], 11, v[0:1]
	v_lshl_add_u64 v[0:1], v[66:67], 0, v[0:1]
	v_add_co_u32_e32 v0, vcc, 0xffffb000, v0
	s_nop 1
	v_addc_co_u32_e32 v1, vcc, -1, v1, vcc
	s_waitcnt vmcnt(0)
	v_and_b32_e32 v5, 0xffff0000, v196
	v_and_b32_e32 v7, 0xffff0000, v197
	v_lshlrev_b32_e32 v4, 16, v196
	v_lshlrev_b32_e32 v6, 16, v197

; __device__ __forceinline__ float bf2f(short b) { return __uint_as_float(((unsigned)(unsigned short)b) << 16); }
; template <int W>
; __device__ __forceinline__ void pool_item(const Params& p, const bf16_t* __restrict__ U, bf16_t* __restrict__ PO, bool samp, int b, int rowb, int t0, int c4) {
;     ...
;     for (int j = 0; j < W + NR - 1; ++j) {
;         const int tp = t0 - W + 1 + j;
;         if (tp >= 0) { const bf16x4 v = *(const bf16x4*)(U + (size_t)(rowb + tp) * DM + c4); r[j] = (f32x4){bf2f(v[0]), bf2f(v[1]), bf2f(v[2]), bf2f(v[3])}; }
;         else if (samp) r[j] = *(const f32x4*)(hist + (size_t)(15 + tp) * 1024 + c4);
;         else r[j] = (f32x4){0.f, 0.f, 0.f, 0.f};
.LBB0_1043:
	s_andn2_saveexec_b64 s[0:1], s[0:1]
	s_cbranch_execz .LBB0_1045
	s_waitcnt vmcnt(0)
	v_add_u32_e32 v0, v101, v76
	v_ashrrev_i32_e32 v1, 31, v0
	v_lshlrev_b64 v[0:1], 11, v[0:1]
	v_lshl_add_u64 v[0:1], v[66:67], 0, v[0:1]
	v_add_co_u32_e32 v0, vcc, 0xffffc000, v0
	s_nop 1
	v_addc_co_u32_e32 v1, vcc, -1, v1, vcc
	s_waitcnt vmcnt(0)
	v_and_b32_e32 v1, 0xffff0000, v198
	v_and_b32_e32 v3, 0xffff0000, v199
	v_lshlrev_b32_e32 v0, 16, v198
	v_lshlrev_b32_e32 v2, 16, v199
.LBB0_1045:
	s_or_b64 exec, exec, s[0:1]
	v_cmp_ne_u32_e64 s[4:5], 0, v101
	s_and_saveexec_b64 s[0:1], s[4:5]
	s_xor_b64 s[0:1], exec, s[0:1]
	s_cbranch_execz .LBB0_1103
	v_add_u32_e32 v28, v101, v76
	v_ashrrev_i32_e32 v29, 31, v28
	v_lshlrev_b64 v[28:29], 11, v[28:29]
	v_lshl_add_u64 v[28:29], v[66:67], 0, v[28:29]
	v_add_co_u32_e32 v28, vcc, 0xffffc000, v28
	s_nop 1
	v_addc_co_u32_e32 v29, vcc, -1, v29, vcc
	s_waitcnt vmcnt(0)
	v_and_b32_e32 v29, 0xffff0000, v200
	v_and_b32_e32 v31, 0xffff0000, v201
	v_lshlrev_b32_e32 v28, 16, v200
	v_lshlrev_b32_e32 v30, 16, v201
	s_andn2_saveexec_b64 s[0:1], s[0:1]
	s_cbranch_execnz .LBB0_1104

; __device__ __forceinline__ float bf2f(short b) { return __uint_as_float(((unsigned)(unsigned short)b) << 16); }
; template <int W>
; __device__ __forceinline__ void pool_item(const Params& p, const bf16_t* __restrict__ U, bf16_t* __restrict__ PO, bool samp, int b, int rowb, int t0, int c4) {
;     ...
;     for (int j = 0; j < W + NR - 1; ++j) {
;         const int tp = t0 - W + 1 + j;
;         if (tp >= 0) { const bf16x4 v = *(const bf16x4*)(U + (size_t)(rowb + tp) * DM + c4); r[j] = (f32x4){bf2f(v[0]), bf2f(v[1]), bf2f(v[2]), bf2f(v[3])}; }
;         else if (samp) r[j] = *(const f32x4*)(hist + (size_t)(15 + tp) * 1024 + c4);
;         else r[j] = (f32x4){0.f, 0.f, 0.f, 0.f};
.LBB0_1048:
	v_add_u32_e32 v32, v101, v76
	v_ashrrev_i32_e32 v33, 31, v32
	v_lshlrev_b64 v[32:33], 11, v[32:33]
	v_lshl_add_u64 v[32:33], v[66:67], 0, v[32:33]
	v_add_co_u32_e32 v32, vcc, 0xffffd000, v32
	s_nop 1
	v_addc_co_u32_e32 v33, vcc, -1, v33, vcc
	s_waitcnt vmcnt(0)
	v_and_b32_e32 v33, 0xffff0000, v202
	v_and_b32_e32 v35, 0xffff0000, v203
	v_lshlrev_b32_e32 v32, 16, v202
	v_lshlrev_b32_e32 v34, 16, v203
	s_andn2_saveexec_b64 s[0:1], s[0:1]
	s_cbranch_execnz .LBB0_1108

; __device__ __forceinline__ float bf2f(short b) { return __uint_as_float(((unsigned)(unsigned short)b) << 16); }
; template <int W>
; __device__ __forceinline__ void pool_item(const Params& p, const bf16_t* __restrict__ U, bf16_t* __restrict__ PO, bool samp, int b, int rowb, int t0, int c4) {
;     ...
;     for (int j = 0; j < W + NR - 1; ++j) {
;         const int tp = t0 - W + 1 + j;
;         if (tp >= 0) { const bf16x4 v = *(const bf16x4*)(U + (size_t)(rowb + tp) * DM + c4); r[j] = (f32x4){bf2f(v[0]), bf2f(v[1]), bf2f(v[2]), bf2f(v[3])}; }
;         else if (samp) r[j] = *(const f32x4*)(hist + (size_t)(15 + tp) * 1024 + c4);
;         else r[j] = (f32x4){0.f, 0.f, 0.f, 0.f};
.LBB0_1050:
	v_add_u32_e32 v36, v101, v76
	v_ashrrev_i32_e32 v37, 31, v36
	v_lshlrev_b64 v[36:37], 11, v[36:37]
	v_lshl_add_u64 v[36:37], v[66:67], 0, v[36:37]
	v_add_co_u32_e32 v36, vcc, 0xffffd000, v36
	s_nop 1
	v_addc_co_u32_e32 v37, vcc, -1, v37, vcc
	s_waitcnt vmcnt(0)
	v_and_b32_e32 v37, 0xffff0000, v204
	v_and_b32_e32 v39, 0xffff0000, v205
	v_lshlrev_b32_e32 v36, 16, v204
	v_lshlrev_b32_e32 v38, 16, v205
	s_andn2_saveexec_b64 s[0:1], s[0:1]
	s_cbranch_execnz .LBB0_1112

; __device__ __forceinline__ float bf2f(short b) { return __uint_as_float(((unsigned)(unsigned short)b) << 16); }
; template <int W>
; __device__ __forceinline__ void pool_item(const Params& p, const bf16_t* __restrict__ U, bf16_t* __restrict__ PO, bool samp, int b, int rowb, int t0, int c4) {
;     ...
;     for (int j = 0; j < W + NR - 1; ++j) {
;         const int tp = t0 - W + 1 + j;
;         if (tp >= 0) { const bf16x4 v = *(const bf16x4*)(U + (size_t)(rowb + tp) * DM + c4); r[j] = (f32x4){bf2f(v[0]), bf2f(v[1]), bf2f(v[2]), bf2f(v[3])}; }
;         else if (samp) r[j] = *(const f32x4*)(hist + (size_t)(15 + tp) * 1024 + c4);
;         else r[j] = (f32x4){0.f, 0.f, 0.f, 0.f};
.LBB0_1052:
	v_add_u32_e32 v40, v101, v76
	v_ashrrev_i32_e32 v41, 31, v40
	v_lshlrev_b64 v[40:41], 11, v[40:41]
	v_lshl_add_u64 v[40:41], v[66:67], 0, v[40:41]
	v_add_co_u32_e32 v40, vcc, 0xffffe000, v40
	s_nop 1
	v_addc_co_u32_e32 v41, vcc, -1, v41, vcc
	s_waitcnt vmcnt(0)
	v_and_b32_e32 v41, 0xffff0000, v206
	v_and_b32_e32 v43, 0xffff0000, v207
	v_lshlrev_b32_e32 v40, 16, v206
	v_lshlrev_b32_e32 v42, 16, v207
	s_andn2_saveexec_b64 s[0:1], s[0:1]
	s_cbranch_execnz .LBB0_1116

; __device__ __forceinline__ float bf2f(short b) { return __uint_as_float(((unsigned)(unsigned short)b) << 16); }
; template <int W>
; __device__ __forceinline__ void pool_item(const Params& p, const bf16_t* __restrict__ U, bf16_t* __restrict__ PO, bool samp, int b, int rowb, int t0, int c4) {
;     ...
;     for (int j = 0; j < W + NR - 1; ++j) {
;         const int tp = t0 - W + 1 + j;
;         if (tp >= 0) { const bf16x4 v = *(const bf16x4*)(U + (size_t)(rowb + tp) * DM + c4); r[j] = (f32x4){bf2f(v[0]), bf2f(v[1]), bf2f(v[2]), bf2f(v[3])}; }
;         else if (samp) r[j] = *(const f32x4*)(hist + (size_t)(15 + tp) * 1024 + c4);
;         else r[j] = (f32x4){0.f, 0.f, 0.f, 0.f};
.LBB0_1054:
	v_add_u32_e32 v44, v101, v76
	v_ashrrev_i32_e32 v45, 31, v44
	v_lshlrev_b64 v[44:45], 11, v[44:45]
	v_lshl_add_u64 v[44:45], v[66:67], 0, v[44:45]
	v_add_co_u32_e32 v44, vcc, 0xffffe000, v44
	s_nop 1
	v_addc_co_u32_e32 v45, vcc, -1, v45, vcc
	s_waitcnt vmcnt(0)
	v_and_b32_e32 v45, 0xffff0000, v208
	v_and_b32_e32 v47, 0xffff0000, v209
	v_lshlrev_b32_e32 v44, 16, v208
	v_lshlrev_b32_e32 v46, 16, v209
	s_andn2_saveexec_b64 s[0:1], s[0:1]
	s_cbranch_execnz .LBB0_1120

; __device__ __forceinline__ float bf2f(short b) { return __uint_as_float(((unsigned)(unsigned short)b) << 16); }
; template <int W>
; __device__ __forceinline__ void pool_item(const Params& p, const bf16_t* __restrict__ U, bf16_t* __restrict__ PO, bool samp, int b, int rowb, int t0, int c4) {
;     ...
;     for (int j = 0; j < W + NR - 1; ++j) {
;         const int tp = t0 - W + 1 + j;
;         if (tp >= 0) { const bf16x4 v = *(const bf16x4*)(U + (size_t)(rowb + tp) * DM + c4); r[j] = (f32x4){bf2f(v[0]), bf2f(v[1]), bf2f(v[2]), bf2f(v[3])}; }
;         else if (samp) r[j] = *(const f32x4*)(hist + (size_t)(15 + tp) * 1024 + c4);
;         else r[j] = (f32x4){0.f, 0.f, 0.f, 0.f};
.LBB0_1056:
	v_add_u32_e32 v48, v101, v76
	v_ashrrev_i32_e32 v49, 31, v48
	v_lshlrev_b64 v[48:49], 11, v[48:49]
	v_lshl_add_u64 v[48:49], v[66:67], 0, v[48:49]
	v_add_co_u32_e32 v48, vcc, 0xfffff000, v48
	s_nop 1
	v_addc_co_u32_e32 v49, vcc, -1, v49, vcc
	s_waitcnt vmcnt(0)
	v_and_b32_e32 v49, 0xffff0000, v210
	v_and_b32_e32 v51, 0xffff0000, v211
	v_lshlrev_b32_e32 v48, 16, v210
	v_lshlrev_b32_e32 v50, 16, v211
	s_andn2_saveexec_b64 s[0:1], s[0:1]
	s_cbranch_execnz .LBB0_1124

; __device__ __forceinline__ float bf2f(short b) { return __uint_as_float(((unsigned)(unsigned short)b) << 16); }
; template <int W>
; __device__ __forceinline__ void pool_item(const Params& p, const bf16_t* __restrict__ U, bf16_t* __restrict__ PO, bool samp, int b, int rowb, int t0, int c4) {
;     ...
;     for (int j = 0; j < W + NR - 1; ++j) {
;         const int tp = t0 - W + 1 + j;
;         if (tp >= 0) { const bf16x4 v = *(const bf16x4*)(U + (size_t)(rowb + tp) * DM + c4); r[j] = (f32x4){bf2f(v[0]), bf2f(v[1]), bf2f(v[2]), bf2f(v[3])}; }
;         else if (samp) r[j] = *(const f32x4*)(hist + (size_t)(15 + tp) * 1024 + c4);
;         else r[j] = (f32x4){0.f, 0.f, 0.f, 0.f};
.LBB0_1058:
	v_add_u32_e32 v52, v101, v76
	v_ashrrev_i32_e32 v53, 31, v52
	v_lshlrev_b64 v[52:53], 11, v[52:53]
	v_lshl_add_u64 v[52:53], v[66:67], 0, v[52:53]
	s_waitcnt vmcnt(0)
	v_and_b32_e32 v53, 0xffff0000, v212
	v_and_b32_e32 v55, 0xffff0000, v213
	v_lshlrev_b32_e32 v52, 16, v212
	v_lshlrev_b32_e32 v54, 16, v213
	s_andn2_saveexec_b64 s[0:1], s[0:1]
	s_cbranch_execz .LBB0_1131
	s_branch .LBB0_1128

; __device__ __forceinline__ float bf2f(short b) { return __uint_as_float(((unsigned)(unsigned short)b) << 16); }
; template <int W>
; __device__ __forceinline__ void pool_item(const Params& p, const bf16_t* __restrict__ U, bf16_t* __restrict__ PO, bool samp, int b, int rowb, int t0, int c4) {
;     ...
;     for (int j = 0; j < W + NR - 1; ++j) {
;         const int tp = t0 - W + 1 + j;
;         if (tp >= 0) { const bf16x4 v = *(const bf16x4*)(U + (size_t)(rowb + tp) * DM + c4); r[j] = (f32x4){bf2f(v[0]), bf2f(v[1]), bf2f(v[2]), bf2f(v[3])}; }
;         else if (samp) r[j] = *(const f32x4*)(hist + (size_t)(15 + tp) * 1024 + c4);
;         else r[j] = (f32x4){0.f, 0.f, 0.f, 0.f};
.LBB0_1172:
	s_andn2_saveexec_b64 s[52:53], s[52:53]
	s_cbranch_execz .LBB0_1252
	v_add_u32_e32 v214, v101, v76
	v_ashrrev_i32_e32 v215, 31, v214
	v_lshlrev_b64 v[214:215], 11, v[214:215]
	v_lshl_add_u64 v[214:215], v[66:67], 0, v[214:215]
	s_mov_b32 s98, 0xffffe000
	s_mov_b32 s99, -1
	global_load_dwordx2 v[212:213], v[214:215], off offset:-4096
	v_lshl_add_u64 v[214:215], v[214:215], 0, s[98:99]
	global_load_dwordx2 v[210:211], v[214:215], off offset:2048
	global_load_dwordx2 v[208:209], v[214:215], off
	global_load_dwordx2 v[206:207], v[214:215], off offset:-2048
	global_load_dwordx2 v[204:205], v[214:215], off offset:-4096
	v_lshl_add_u64 v[214:215], v[214:215], 0, s[98:99]
	global_load_dwordx2 v[202:203], v[214:215], off offset:2048
	v_cmp_ne_u32_e64 s[4:5], 0, v101
	s_and_saveexec_b64 s[0:1], s[4:5]
	s_xor_b64 s[0:1], exec, s[0:1]
	s_cbranch_execz .LBB0_1187
	v_add_u32_e32 v0, v101, v76
	v_ashrrev_i32_e32 v1, 31, v0
	v_lshlrev_b64 v[0:1], 11, v[0:1]
	v_lshl_add_u64 v[0:1], v[66:67], 0, v[0:1]
	v_add_co_u32_e32 v0, vcc, 0xffffd000, v0
	s_nop 1
	v_addc_co_u32_e32 v1, vcc, -1, v1, vcc
	s_waitcnt vmcnt(0)
	v_and_b32_e32 v25, 0xffff0000, v202
	v_and_b32_e32 v27, 0xffff0000, v203
	v_lshlrev_b32_e32 v24, 16, v202
	v_lshlrev_b32_e32 v26, 16, v203
	s_andn2_saveexec_b64 s[0:1], s[0:1]
	s_cbranch_execnz .LBB0_1188

; __device__ __forceinline__ float bf2f(short b) { return __uint_as_float(((unsigned)(unsigned short)b) << 16); }
; template <int W>
; __device__ __forceinline__ void pool_item(const Params& p, const bf16_t* __restrict__ U, bf16_t* __restrict__ PO, bool samp, int b, int rowb, int t0, int c4) {
;     ...
;     for (int j = 0; j < W + NR - 1; ++j) {
;         const int tp = t0 - W + 1 + j;
;         if (tp >= 0) { const bf16x4 v = *(const bf16x4*)(U + (size_t)(rowb + tp) * DM + c4); r[j] = (f32x4){bf2f(v[0]), bf2f(v[1]), bf2f(v[2]), bf2f(v[3])}; }
;         else if (samp) r[j] = *(const f32x4*)(hist + (size_t)(15 + tp) * 1024 + c4);
;         else r[j] = (f32x4){0.f, 0.f, 0.f, 0.f};
.LBB0_1176:
	v_add_u32_e32 v0, v101, v76
	v_ashrrev_i32_e32 v1, 31, v0
	v_lshlrev_b64 v[0:1], 11, v[0:1]
	v_lshl_add_u64 v[0:1], v[66:67], 0, v[0:1]
	v_add_co_u32_e32 v0, vcc, 0xffffd000, v0
	s_nop 1
	v_addc_co_u32_e32 v1, vcc, -1, v1, vcc
	s_waitcnt vmcnt(0)
	v_and_b32_e32 v21, 0xffff0000, v204
	v_and_b32_e32 v23, 0xffff0000, v205
	v_lshlrev_b32_e32 v20, 16, v204
	v_lshlrev_b32_e32 v22, 16, v205
	s_andn2_saveexec_b64 s[0:1], s[0:1]
	s_cbranch_execnz .LBB0_1192

; __device__ __forceinline__ float bf2f(short b) { return __uint_as_float(((unsigned)(unsigned short)b) << 16); }
; template <int W>
; __device__ __forceinline__ void pool_item(const Params& p, const bf16_t* __restrict__ U, bf16_t* __restrict__ PO, bool samp, int b, int rowb, int t0, int c4) {
;     ...
;     for (int j = 0; j < W + NR - 1; ++j) {
;         const int tp = t0 - W + 1 + j;
;         if (tp >= 0) { const bf16x4 v = *(const bf16x4*)(U + (size_t)(rowb + tp) * DM + c4); r[j] = (f32x4){bf2f(v[0]), bf2f(v[1]), bf2f(v[2]), bf2f(v[3])}; }
;         else if (samp) r[j] = *(const f32x4*)(hist + (size_t)(15 + tp) * 1024 + c4);
;         else r[j] = (f32x4){0.f, 0.f, 0.f, 0.f};
.LBB0_1178:
	v_add_u32_e32 v0, v101, v76
	v_ashrrev_i32_e32 v1, 31, v0
	v_lshlrev_b64 v[0:1], 11, v[0:1]
	v_lshl_add_u64 v[0:1], v[66:67], 0, v[0:1]
	v_add_co_u32_e32 v0, vcc, 0xffffe000, v0
	s_nop 1
	v_addc_co_u32_e32 v1, vcc, -1, v1, vcc
	s_waitcnt vmcnt(0)
	v_and_b32_e32 v17, 0xffff0000, v206
	v_and_b32_e32 v19, 0xffff0000, v207
	v_lshlrev_b32_e32 v16, 16, v206
	v_lshlrev_b32_e32 v18, 16, v207
	s_andn2_saveexec_b64 s[0:1], s[0:1]
	s_cbranch_execnz .LBB0_1196

; __device__ __forceinline__ float bf2f(short b) { return __uint_as_float(((unsigned)(unsigned short)b) << 16); }
; template <int W>
; __device__ __forceinline__ void pool_item(const Params& p, const bf16_t* __restrict__ U, bf16_t* __restrict__ PO, bool samp, int b, int rowb, int t0, int c4) {
;     ...
;     for (int j = 0; j < W + NR - 1; ++j) {
;         const int tp = t0 - W + 1 + j;
;         if (tp >= 0) { const bf16x4 v = *(const bf16x4*)(U + (size_t)(rowb + tp) * DM + c4); r[j] = (f32x4){bf2f(v[0]), bf2f(v[1]), bf2f(v[2]), bf2f(v[3])}; }
;         else if (samp) r[j] = *(const f32x4*)(hist + (size_t)(15 + tp) * 1024 + c4);
;         else r[j] = (f32x4){0.f, 0.f, 0.f, 0.f};
.LBB0_1180:
	v_add_u32_e32 v0, v101, v76
	v_ashrrev_i32_e32 v1, 31, v0
	v_lshlrev_b64 v[0:1], 11, v[0:1]
	v_lshl_add_u64 v[0:1], v[66:67], 0, v[0:1]
	v_add_co_u32_e32 v0, vcc, 0xffffe000, v0
	s_nop 1
	v_addc_co_u32_e32 v1, vcc, -1, v1, vcc
	s_waitcnt vmcnt(0)
	v_and_b32_e32 v13, 0xffff0000, v208
	v_and_b32_e32 v15, 0xffff0000, v209
	v_lshlrev_b32_e32 v12, 16, v208
	v_lshlrev_b32_e32 v14, 16, v209
	s_andn2_saveexec_b64 s[0:1], s[0:1]
	s_cbranch_execnz .LBB0_1200

; __device__ __forceinline__ float bf2f(short b) { return __uint_as_float(((unsigned)(unsigned short)b) << 16); }
; template <int W>
; __device__ __forceinline__ void pool_item(const Params& p, const bf16_t* __restrict__ U, bf16_t* __restrict__ PO, bool samp, int b, int rowb, int t0, int c4) {
;     ...
;     for (int j = 0; j < W + NR - 1; ++j) {
;         const int tp = t0 - W + 1 + j;
;         if (tp >= 0) { const bf16x4 v = *(const bf16x4*)(U + (size_t)(rowb + tp) * DM + c4); r[j] = (f32x4){bf2f(v[0]), bf2f(v[1]), bf2f(v[2]), bf2f(v[3])}; }
;         else if (samp) r[j] = *(const f32x4*)(hist + (size_t)(15 + tp) * 1024 + c4);
;         else r[j] = (f32x4){0.f, 0.f, 0.f, 0.f};
.LBB0_1182:
	v_add_u32_e32 v0, v101, v76
	v_ashrrev_i32_e32 v1, 31, v0
	v_lshlrev_b64 v[0:1], 11, v[0:1]
	v_lshl_add_u64 v[0:1], v[66:67], 0, v[0:1]
	v_add_co_u32_e32 v0, vcc, 0xfffff000, v0
	s_nop 1
	v_addc_co_u32_e32 v1, vcc, -1, v1, vcc
	s_waitcnt vmcnt(0)
	v_and_b32_e32 v9, 0xffff0000, v210
	v_and_b32_e32 v11, 0xffff0000, v211
	v_lshlrev_b32_e32 v8, 16, v210
	v_lshlrev_b32_e32 v10, 16, v211
	s_andn2_saveexec_b64 s[0:1], s[0:1]
	s_cbranch_execnz .LBB0_1204

; __device__ __forceinline__ float bf2f(short b) { return __uint_as_float(((unsigned)(unsigned short)b) << 16); }
; template <int W>
; __device__ __forceinline__ void pool_item(const Params& p, const bf16_t* __restrict__ U, bf16_t* __restrict__ PO, bool samp, int b, int rowb, int t0, int c4) {
;     ...
;     for (int j = 0; j < W + NR - 1; ++j) {
;         const int tp = t0 - W + 1 + j;
;         if (tp >= 0) { const bf16x4 v = *(const bf16x4*)(U + (size_t)(rowb + tp) * DM + c4); r[j] = (f32x4){bf2f(v[0]), bf2f(v[1]), bf2f(v[2]), bf2f(v[3])}; }
;         else if (samp) r[j] = *(const f32x4*)(hist + (size_t)(15 + tp) * 1024 + c4);
;         else r[j] = (f32x4){0.f, 0.f, 0.f, 0.f};
.LBB0_1184:
	v_add_u32_e32 v0, v101, v76
	v_ashrrev_i32_e32 v1, 31, v0
	v_lshlrev_b64 v[0:1], 11, v[0:1]
	v_lshl_add_u64 v[0:1], v[66:67], 0, v[0:1]
	s_waitcnt vmcnt(0)
	v_and_b32_e32 v1, 0xffff0000, v212
	v_and_b32_e32 v3, 0xffff0000, v213
	v_lshlrev_b32_e32 v0, 16, v212
	v_lshlrev_b32_e32 v2, 16, v213
	s_andn2_saveexec_b64 s[0:1], s[0:1]
	s_cbranch_execz .LBB0_1211
	s_branch .LBB0_1208

; __device__ __forceinline__ float bf2f(short b) { return __uint_as_float(((unsigned)(unsigned short)b) << 16); }
; template <int W>
; __device__ __forceinline__ void pool_item(const Params& p, const bf16_t* __restrict__ U, bf16_t* __restrict__ PO, bool samp, int b, int rowb, int t0, int c4) {
;     ...
;     for (int j = 0; j < W + NR - 1; ++j) {
;         const int tp = t0 - W + 1 + j;
;         if (tp >= 0) { const bf16x4 v = *(const bf16x4*)(U + (size_t)(rowb + tp) * DM + c4); r[j] = (f32x4){bf2f(v[0]), bf2f(v[1]), bf2f(v[2]), bf2f(v[3])}; }
;         else if (samp) r[j] = *(const f32x4*)(hist + (size_t)(15 + tp) * 1024 + c4);
;         else r[j] = (f32x4){0.f, 0.f, 0.f, 0.f};
.LBB0_1253:
	s_andn2_saveexec_b64 s[46:47], s[46:47]
	s_cbranch_execz .LBB0_1307
	v_add_u32_e32 v214, v101, v76
	v_ashrrev_i32_e32 v215, 31, v214
	v_lshlrev_b64 v[214:215], 11, v[214:215]
	v_lshl_add_u64 v[214:215], v[66:67], 0, v[214:215]
	s_mov_b32 s98, 0xffffe000
	s_mov_b32 s99, -1
	global_load_dwordx2 v[212:213], v[214:215], off offset:-4096
	v_lshl_add_u64 v[214:215], v[214:215], 0, s[98:99]
	global_load_dwordx2 v[210:211], v[214:215], off offset:2048
	v_cmp_ne_u32_e64 s[4:5], 0, v101
	s_and_saveexec_b64 s[0:1], s[4:5]
	s_xor_b64 s[0:1], exec, s[0:1]
	s_cbranch_execz .LBB0_1258
	v_add_u32_e32 v0, v101, v76
	v_ashrrev_i32_e32 v1, 31, v0
	v_lshlrev_b64 v[0:1], 11, v[0:1]
	v_lshl_add_u64 v[0:1], v[66:67], 0, v[0:1]
	v_add_co_u32_e32 v0, vcc, 0xfffff000, v0
	s_nop 1
	v_addc_co_u32_e32 v1, vcc, -1, v1, vcc
	s_waitcnt vmcnt(0)
	v_and_b32_e32 v9, 0xffff0000, v210
	v_and_b32_e32 v11, 0xffff0000, v211
	v_lshlrev_b32_e32 v8, 16, v210
	v_lshlrev_b32_e32 v10, 16, v211
	s_andn2_saveexec_b64 s[0:1], s[0:1]
	s_cbranch_execnz .LBB0_1259

; __device__ __forceinline__ float bf2f(short b) { return __uint_as_float(((unsigned)(unsigned short)b) << 16); }
; template <int W>
; __device__ __forceinline__ void pool_item(const Params& p, const bf16_t* __restrict__ U, bf16_t* __restrict__ PO, bool samp, int b, int rowb, int t0, int c4) {
;     ...
;     for (int j = 0; j < W + NR - 1; ++j) {
;         const int tp = t0 - W + 1 + j;
;         if (tp >= 0) { const bf16x4 v = *(const bf16x4*)(U + (size_t)(rowb + tp) * DM + c4); r[j] = (f32x4){bf2f(v[0]), bf2f(v[1]), bf2f(v[2]), bf2f(v[3])}; }
;         else if (samp) r[j] = *(const f32x4*)(hist + (size_t)(15 + tp) * 1024 + c4);
;         else r[j] = (f32x4){0.f, 0.f, 0.f, 0.f};
.LBB0_1257:
	v_add_u32_e32 v0, v101, v76
	v_ashrrev_i32_e32 v1, 31, v0
	v_lshlrev_b64 v[0:1], 11, v[0:1]
	v_lshl_add_u64 v[0:1], v[66:67], 0, v[0:1]
	s_waitcnt vmcnt(0)
	v_and_b32_e32 v5, 0xffff0000, v212
	v_and_b32_e32 v7, 0xffff0000, v213
	v_lshlrev_b32_e32 v4, 16, v212
	v_lshlrev_b32_e32 v6, 16, v213
	s_andn2_saveexec_b64 s[0:1], s[0:1]
	s_cbranch_execz .LBB0_1266
	s_branch .LBB0_1263
